# attention A even step: K fragment LDS reads issued one head-dim slice ahead of their MFMAs (second register pair)
# speedup vs baseline: 1.0079x; 1.0039x over previous
; template <int OFF> __device__ __forceinline__ s16x4 tr_read(int vb) { s16x4 r; asm volatile("ds_read_b64_tr_b16 %0, %1 offset:%2" : "=&v"(r) : "v"(vb), "i"(OFF) : "memory"); return r; }
; __device__ __forceinline__ void finishSM(f32x16& p0, f32x16& p1, float alpha, float& l_reg, bf16x8& pa0, bf16x8& pa1, bf16x8& pa2, bf16x8& pa3) {
; #pragma unroll
;   for (int r = 0; r < 16; ++r) p1[r] = __builtin_amdgcn_exp2f(p1[r]);
;   float ps = 0;
; #pragma unroll
;   for (int r = 0; r < 16; ++r) ps += p0[r];
; #pragma unroll
;   for (int r = 0; r < 16; ++r) ps += p1[r];
;   { auto rr = __builtin_amdgcn_permlane32_swap(__float_as_uint(ps), __float_as_uint(ps), false, false);
;     ps = __uint_as_float(rr[0]) + __uint_as_float(rr[1]); }
;   l_reg = l_reg * alpha + ps;
;     ...
;   ATT_PKN(p0, 0, pa0); ATT_PKN(p0, 8, pa1); ATT_PKN(p1, 0, pa2); ATT_PKN(p1, 8, pa3);
;     ...
; }
; __device__ __forceinline__ void qkt(f32x16& p0, f32x16& p1, const bf16* Ks, const bf16x8* qr, int r32, int hi, int mp, const f32x16& negm) {
; #pragma unroll
;   for (int d0 = 0; d0 < 4; ++d0) { int cb = ((mp * 4 + d0) * 16 + hi * 8) * 2;
;     bf16x8 b0 = *reinterpret_cast<const bf16x8*>((const char*)Ks + KSWZ(r32, cb));
;     bf16x8 b1 = *reinterpret_cast<const bf16x8*>((const char*)Ks + KSWZ(32 + r32, cb));
;     if (d0 == 0) { p0 = __builtin_amdgcn_mfma_f32_32x32x16_bf16(b0, qr[0], negm, 0, 0, 0); p1 = __builtin_amdgcn_mfma_f32_32x32x16_bf16(b1, qr[0], negm, 0, 0, 0); }
;     else { p0 = __builtin_amdgcn_mfma_f32_32x32x16_bf16(b0, qr[d0], p0, 0, 0, 0); p1 = __builtin_amdgcn_mfma_f32_32x32x16_bf16(b1, qr[d0], p1, 0, 0, 0); } }
; }
; __device__ __forceinline__ int v_st(int k, int c) { const int kk = k; return ((kk >> 3) * 4 + (c >> 5)) * 512 + ((kk & 7) * 32 + (c & 31)) * 2; }
; template <int D0> __device__ __forceinline__ void pv_one(f32x16& od, int vb, bf16x8 pa0, bf16x8 pa1, bf16x8 pa2, bf16x8 pa3) {
;   const s16x4 l0 = tr_read<v_rd_off(D0, 0, 0)>(vb), h0 = tr_read<v_rd_off(D0, 0, 1)>(vb), l1 = tr_read<v_rd_off(D0, 1, 0)>(vb), h1 = tr_read<v_rd_off(D0, 1, 1)>(vb);
;   const s16x4 l2 = tr_read<v_rd_off(D0, 2, 0)>(vb), h2 = tr_read<v_rd_off(D0, 2, 1)>(vb), l3 = tr_read<v_rd_off(D0, 3, 0)>(vb), h3 = tr_read<v_rd_off(D0, 3, 1)>(vb);
.LBB0_197:
	s_add_i32 s10, s39, 0
	v_add_u32_e32 v112, s10, v202
	ds_read_b128 v[236:239], v112 offset:24576
	ds_read_b128 v[112:115], v112 offset:16384
	v_add_u32_e32 v208, s10, v201
	ds_read_b128 v[68:71], v208 offset:24576
	ds_read_b128 v[72:75], v208 offset:16384
	v_add_u32_e32 v208, s10, v199
	v_exp_f32_e32 v210, v96
	v_add_f32_e32 v96, 0, v172
	v_add_f32_e32 v96, v174, v96
	s_waitcnt lgkmcnt(2)
	v_mfma_f32_32x32x16_bf16 v[128:143], v[112:115], v[158:161], v[80:95]
	v_mov_b64_e32 v[126:127], v[94:95]
	v_mov_b64_e32 v[124:125], v[92:93]
	v_mov_b64_e32 v[122:123], v[90:91]
	v_mov_b64_e32 v[120:121], v[88:89]
	v_mov_b64_e32 v[118:119], v[86:87]
	v_mov_b64_e32 v[116:117], v[84:85]
	v_mov_b64_e32 v[114:115], v[82:83]
	v_mov_b64_e32 v[112:113], v[80:81]
	v_add_f32_e32 v96, v175, v96
	v_add_f32_e32 v96, v211, v96
	v_mfma_f32_32x32x16_bf16 v[112:127], v[236:239], v[158:161], v[112:127]
	ds_read_b128 v[236:239], v208 offset:24576
	ds_read_b128 v[240:243], v208 offset:16384
	v_add_u32_e32 v208, s10, v183
	v_add_f32_e32 v96, v212, v96
	v_add_f32_e32 v96, v215, v96
	v_add_f32_e32 v96, v216, v96
	v_add_f32_e32 v96, v233, v96
	v_add_f32_e32 v96, v173, v96
	s_waitcnt lgkmcnt(2)
	v_mfma_f32_32x32x16_bf16 v[112:127], v[68:71], v[154:157], v[112:127]
	v_add_f32_e32 v96, v176, v96
	v_add_f32_e32 v96, v177, v96
	v_add_f32_e32 v96, v213, v96
	v_add_f32_e32 v96, v214, v96
	v_exp_f32_e32 v235, v97
	v_add_f32_e32 v96, v217, v96
	v_add_f32_e32 v96, v232, v96
	v_mfma_f32_32x32x16_bf16 v[128:143], v[72:75], v[154:157], v[128:143]
	ds_read_b128 v[68:71], v208 offset:24576
	ds_read_b128 v[72:75], v208 offset:16384
	v_add_f32_e32 v96, v234, v96
	v_add_f32_e32 v96, v210, v96
	v_add_f32_e32 v96, v235, v96
	v_exp_f32_e32 v244, v106
	v_exp_f32_e32 v245, v107
	s_waitcnt lgkmcnt(2)
	v_mfma_f32_32x32x16_bf16 v[112:127], v[236:239], v[150:153], v[112:127]
	v_exp_f32_e32 v246, v108
	v_exp_f32_e32 v247, v109
	v_exp_f32_e32 v248, v110
	v_exp_f32_e32 v111, v111
	v_cvt_pk_bf16_f32 v97, v175, v211
	v_cvt_pk_bf16_f32 v109, v244, v245
	v_cvt_pk_bf16_f32 v110, v246, v247
	v_mfma_f32_32x32x16_bf16 v[128:143], v[240:243], v[150:153], v[128:143]
	s_waitcnt lgkmcnt(0)
	v_mfma_f32_32x32x16_bf16 v[112:127], v[68:71], v[146:149], v[112:127]
	v_exp_f32_e32 v236, v98
	v_exp_f32_e32 v237, v99
	v_exp_f32_e32 v238, v100
	v_exp_f32_e32 v239, v101
	v_add_f32_e32 v96, v236, v96
	v_add_f32_e32 v96, v237, v96
	v_add_f32_e32 v96, v238, v96
	v_mfma_f32_32x32x16_bf16 v[128:143], v[72:75], v[146:149], v[128:143]
	v_exp_f32_e32 v240, v102
	v_exp_f32_e32 v241, v103
	v_exp_f32_e32 v242, v104
	v_exp_f32_e32 v243, v105
	v_add_f32_e32 v96, v239, v96
	v_add_f32_e32 v96, v240, v96
	v_add_f32_e32 v96, v241, v96
	v_add_f32_e32 v96, v242, v96
	v_add_f32_e32 v96, v243, v96
	v_add_f32_e32 v96, v244, v96
	v_add_f32_e32 v96, v245, v96
	v_add_f32_e32 v96, v246, v96
	v_add_f32_e32 v96, v247, v96
	v_add_f32_e32 v96, v248, v96
	v_add_f32_e32 v208, v111, v96
	v_mov_b32_e32 v209, v208
	s_nop 1
	v_permlane32_swap_b32_e32 v208, v209
	v_cvt_pk_bf16_f32 v96, v172, v174
	v_cvt_pk_bf16_f32 v98, v212, v215
	v_cvt_pk_bf16_f32 v99, v216, v233
	v_cvt_pk_bf16_f32 v100, v173, v176
	v_cvt_pk_bf16_f32 v101, v177, v213
	v_cvt_pk_bf16_f32 v102, v214, v217
	v_cvt_pk_bf16_f32 v103, v232, v234
	v_cvt_pk_bf16_f32 v104, v210, v235
	v_cvt_pk_bf16_f32 v105, v236, v237
	v_cvt_pk_bf16_f32 v106, v238, v239
	v_cvt_pk_bf16_f32 v107, v240, v241
	v_cvt_pk_bf16_f32 v108, v242, v243
	v_cvt_pk_bf16_f32 v111, v248, v111
	v_add_u32_e32 v240, s48, v205
	ds_read_b64_tr_b16 v[210:211], v240 offset:0
	ds_read_b64_tr_b16 v[212:213], v240 offset:0x800
	ds_read_b64_tr_b16 v[214:215], v240 offset:0x1000
	ds_read_b64_tr_b16 v[216:217], v240 offset:0x1800
	ds_read_b64_tr_b16 v[232:233], v240 offset:0x2000
	ds_read_b64_tr_b16 v[234:235], v240 offset:0x2800
	ds_read_b64_tr_b16 v[236:237], v240 offset:0x3000
	ds_read_b64_tr_b16 v[238:239], v240 offset:0x3800
	v_lshl_add_u64 v[174:175], s[50:51], 0, v[168:169]
	s_add_i32 s12, s21, s56
	v_lshl_add_u64 v[172:173], v[174:175], 0, s[36:37]
	s_add_i32 m0, s12, 0x4000
	s_mov_b64 s[10:11], 0x4030000
	global_load_lds_dwordx4 v[172:173], off
	v_lshl_add_u64 v[172:173], s[50:51], 0, v[188:189]
	v_lshl_add_u64 v[176:177], v[172:173], 0, s[10:11]
	s_mov_b32 m0, s12
	s_mov_b64 s[10:11], 0x4030080
	global_load_lds_dwordx4 v[176:177], off
	v_lshl_add_u64 v[176:177], s[50:51], 0, v[170:171]
	v_lshl_add_u64 v[66:67], v[176:177], 0, s[36:37]
	s_add_i32 m0, s12, 0x4400
	s_nop 0
	global_load_lds_dwordx4 v[66:67], off
	v_lshl_add_u64 v[66:67], v[172:173], 0, s[10:11]
	s_add_i32 m0, s12, 0x400
	s_nop 0
	global_load_lds_dwordx4 v[66:67], off
	s_waitcnt lgkmcnt(0)
; #define SBAR() __builtin_amdgcn_sched_barrier(0)
; template <int OFF> __device__ __forceinline__ s16x4 tr_read(int vb) { s16x4 r; asm volatile("ds_read_b64_tr_b16 %0, %1 offset:%2" : "=&v"(r) : "v"(vb), "i"(OFF) : "memory"); return r; }
; template <bool FIRST> __device__ __forceinline__ void partialSM(f32x16& p0, f32x16& p1, float& m_reg, f32x16& negm, float& alpha) {
;   float pmax = p0[0];
; #pragma unroll
;   for (int r = 1; r < 16; ++r) pmax = fmaxf(pmax, p0[r]);
; #pragma unroll
;   for (int r = 0; r < 16; ++r) pmax = fmaxf(pmax, p1[r]);
;   { auto rr = __builtin_amdgcn_permlane32_swap(__float_as_uint(pmax), __float_as_uint(pmax), false, false);
;     pmax = fmaxf(__uint_as_float(rr[0]), __uint_as_float(rr[1])); }
;   alpha = 1.f;
;   if (FIRST || __builtin_expect(__any(pmax > THR), 0)) { const float dl = FIRST ? pmax : fmaxf(pmax, 0.f); m_reg += dl; if (!FIRST) alpha = __builtin_amdgcn_exp2f(-dl);
; template <int D0> __device__ __forceinline__ void pv_one(f32x16& od, int vb, bf16x8 pa0, bf16x8 pa1, bf16x8 pa2, bf16x8 pa3) {
;   const s16x4 l0 = tr_read<v_rd_off(D0, 0, 0)>(vb), h0 = tr_read<v_rd_off(D0, 0, 1)>(vb), l1 = tr_read<v_rd_off(D0, 1, 0)>(vb), h1 = tr_read<v_rd_off(D0, 1, 1)>(vb);
;   const s16x4 l2 = tr_read<v_rd_off(D0, 2, 0)>(vb), h2 = tr_read<v_rd_off(D0, 2, 1)>(vb), l3 = tr_read<v_rd_off(D0, 3, 0)>(vb), h3 = tr_read<v_rd_off(D0, 3, 1)>(vb);
;   asm volatile("s_waitcnt lgkmcnt(0)" ::: "memory"); SBAR();
;   od = __builtin_amdgcn_mfma_f32_32x32x16_bf16(pa0, ATT_PK(l0, h0), od, 0, 0, 0);
;   od = __builtin_amdgcn_mfma_f32_32x32x16_bf16(pa1, ATT_PK(l1, h1), od, 0, 0, 0);
;   od = __builtin_amdgcn_mfma_f32_32x32x16_bf16(pa2, ATT_PK(l2, h2), od, 0, 0, 0);
;   od = __builtin_amdgcn_mfma_f32_32x32x16_bf16(pa3, ATT_PK(l3, h3), od, 0, 0, 0);
; }
; __device__ __forceinline__ void pv_d0(f32x16* o, int vb, bf16x8 pa0, bf16x8 pa1, bf16x8 pa2, bf16x8 pa3) {
;   pv_one<0>(o[0], vb, pa0, pa1, pa2, pa3); pv_one<1>(o[1], vb, pa0, pa1, pa2, pa3); pv_one<2>(o[2], vb, pa0, pa1, pa2, pa3); pv_one<3>(o[3], vb, pa0, pa1, pa2, pa3);
; }
	s_nop 0
	v_mfma_f32_32x32x16_bf16 v[0:15], v[96:99], v[210:213], v[0:15]
	ds_read_b64_tr_b16 v[210:211], v240 offset:0x200
	ds_read_b64_tr_b16 v[212:213], v240 offset:0xa00
	v_mfma_f32_32x32x16_bf16 v[0:15], v[100:103], v[214:217], v[0:15]
	ds_read_b64_tr_b16 v[214:215], v240 offset:0x1200
	ds_read_b64_tr_b16 v[216:217], v240 offset:0x1a00
	v_mfma_f32_32x32x16_bf16 v[0:15], v[104:107], v[232:235], v[0:15]
	ds_read_b64_tr_b16 v[232:233], v240 offset:0x2200
	ds_read_b64_tr_b16 v[234:235], v240 offset:0x2a00
	v_mfma_f32_32x32x16_bf16 v[0:15], v[108:111], v[236:239], v[0:15]
	ds_read_b64_tr_b16 v[236:237], v240 offset:0x3200
	ds_read_b64_tr_b16 v[238:239], v240 offset:0x3a00
	s_waitcnt lgkmcnt(0)
	v_mfma_f32_32x32x16_bf16 v[48:63], v[96:99], v[210:213], v[48:63]
	ds_read_b64_tr_b16 v[210:211], v240 offset:0x400
	ds_read_b64_tr_b16 v[212:213], v240 offset:0xc00
	v_mfma_f32_32x32x16_bf16 v[48:63], v[100:103], v[214:217], v[48:63]
	ds_read_b64_tr_b16 v[214:215], v240 offset:0x1400
	ds_read_b64_tr_b16 v[216:217], v240 offset:0x1c00
	v_mfma_f32_32x32x16_bf16 v[48:63], v[104:107], v[232:235], v[48:63]
	ds_read_b64_tr_b16 v[232:233], v240 offset:0x2400
	ds_read_b64_tr_b16 v[234:235], v240 offset:0x2c00
	v_mfma_f32_32x32x16_bf16 v[48:63], v[108:111], v[236:239], v[48:63]
	ds_read_b64_tr_b16 v[236:237], v240 offset:0x3400
	ds_read_b64_tr_b16 v[238:239], v240 offset:0x3c00
	s_waitcnt lgkmcnt(0)
	v_mfma_f32_32x32x16_bf16 v[32:47], v[96:99], v[210:213], v[32:47]
	ds_read_b64_tr_b16 v[210:211], v240 offset:0x600
	ds_read_b64_tr_b16 v[212:213], v240 offset:0xe00
	v_mfma_f32_32x32x16_bf16 v[32:47], v[100:103], v[214:217], v[32:47]
	ds_read_b64_tr_b16 v[214:215], v240 offset:0x1600
	ds_read_b64_tr_b16 v[216:217], v240 offset:0x1e00
	v_mfma_f32_32x32x16_bf16 v[32:47], v[104:107], v[232:235], v[32:47]
	ds_read_b64_tr_b16 v[232:233], v240 offset:0x2600
	ds_read_b64_tr_b16 v[234:235], v240 offset:0x2e00
	v_mfma_f32_32x32x16_bf16 v[32:47], v[108:111], v[236:239], v[32:47]
	ds_read_b64_tr_b16 v[236:237], v240 offset:0x3600
	ds_read_b64_tr_b16 v[238:239], v240 offset:0x3e00
	s_waitcnt lgkmcnt(0)
	v_mfma_f32_32x32x16_bf16 v[16:31], v[96:99], v[210:213], v[16:31]
	v_max_f32_e32 v96, v129, v129
	v_max_f32_e32 v97, v128, v128
	v_max_f32_e32 v96, v97, v96
	v_max3_f32 v96, v96, v130, v131
	v_max3_f32 v96, v96, v132, v133
	v_max3_f32 v96, v96, v134, v135
	v_max3_f32 v96, v96, v136, v137
	v_mfma_f32_32x32x16_bf16 v[16:31], v[100:103], v[214:217], v[16:31]
	v_max3_f32 v96, v96, v138, v139
	v_max3_f32 v96, v96, v140, v141
	v_max3_f32 v96, v96, v142, v143
	v_max3_f32 v96, v96, v112, v113
	v_max3_f32 v96, v96, v114, v115
	v_max3_f32 v96, v96, v116, v117
	v_max3_f32 v96, v96, v118, v119
	v_mfma_f32_32x32x16_bf16 v[16:31], v[104:107], v[232:235], v[16:31]
	v_max3_f32 v96, v96, v120, v121
	v_max3_f32 v96, v96, v122, v123
	v_max3_f32 v96, v96, v124, v125
	v_max3_f32 v96, v96, v126, v127
	v_mov_b32_e32 v97, v96
	s_nop 1
	v_permlane32_swap_b32_e32 v96, v97
	v_mfma_f32_32x32x16_bf16 v[16:31], v[108:111], v[236:239], v[16:31]
	v_max_f32_e32 v97, v97, v97
	v_max_f32_e32 v96, v96, v96
	v_max_f32_e32 v96, v96, v97
	v_cmp_lt_f32_e32 vcc, s19, v96
	s_cbranch_vccnz .LBB0_215
	v_mov_b64_e32 v[64:65], v[80:81]
	v_mov_b64_e32 v[66:67], v[82:83]
	v_mov_b64_e32 v[68:69], v[84:85]
	v_mov_b64_e32 v[70:71], v[86:87]
	v_mov_b64_e32 v[72:73], v[88:89]
	v_mov_b64_e32 v[74:75], v[90:91]
	v_mov_b64_e32 v[76:77], v[92:93]
	v_mov_b64_e32 v[78:79], v[94:95]
	v_mov_b32_e32 v210, 1.0
	v_cmp_gt_f32_e32 vcc, 1.0, v210
	s_cbranch_vccz .LBB0_202
